# final_norm: next row's loads prefetched one iteration ahead; row reduction by DPP + permlane swaps instead of 6 ds_bpermute
# baseline (speedup 1.0000x reference)
.LBB7_1426:
	s_cmp_lt_i32 s87, 31
	s_cselect_b64 s[0:1], -1, 0
	s_cmp_gt_i32 s89, 30
	s_cselect_b64 s[2:3], -1, 0
	s_and_b64 s[0:1], s[0:1], s[2:3]
	s_and_b64 vcc, exec, s[0:1]
	v_readlane_b32 s12, v251, 8
	v_readlane_b32 s13, v251, 9
	s_cbranch_vccz .LBB7_1432
	v_readlane_b32 s0, v251, 0
	v_readlane_b32 s1, v251, 1
	s_cmpk_gt_i32 s12, 0x7fff
	v_writelane_b32 v251, s0, 0
	s_nop 1
	v_writelane_b32 v251, s1, 1
	s_cbranch_scc1 .LBB7_1432
	v_readlane_b32 s0, v251, 0
	v_readlane_b32 s1, v251, 1
	s_load_dwordx4 s[4:7], s[0:1], 0x110
	s_load_dwordx2 s[2:3], s[0:1], 0x120
	s_waitcnt vmcnt(0)
	v_lshlrev_b32_e32 v20, 5, v201
	v_and_b32_e32 v16, 64, v163
	v_add_u32_e32 v16, 64, v16
	s_waitcnt lgkmcnt(0)
	global_load_dwordx4 v[0:3], v20, s[4:5] offset:16
	global_load_dwordx4 v[4:7], v20, s[4:5]
	global_load_dwordx4 v[8:11], v20, s[4:5] offset:2064
	global_load_dwordx4 v[12:15], v20, s[4:5] offset:2048
	v_xor_b32_e32 v17, 1, v163
	v_cmp_lt_i32_e32 vcc, v17, v16
	s_ashr_i32 s13, s12, 31
	s_lshl_b64 s[0:1], s[12:13], 6
	v_cndmask_b32_e32 v17, v163, v17, vcc
	v_lshlrev_b32_e32 v22, 2, v17
	v_xor_b32_e32 v17, 2, v163
	v_cmp_lt_i32_e32 vcc, v17, v16
	s_add_u32 s0, s2, s0
	v_readlane_b32 s14, v251, 6
	v_cndmask_b32_e32 v17, v163, v17, vcc
	v_lshlrev_b32_e32 v23, 2, v17
	v_xor_b32_e32 v17, 4, v163
	v_cmp_lt_i32_e32 vcc, v17, v16
	v_lshlrev_b32_e32 v28, 2, v201
	v_mov_b32_e32 v29, 0
	v_cndmask_b32_e32 v17, v163, v17, vcc
	v_lshlrev_b32_e32 v24, 2, v17
	v_xor_b32_e32 v17, 8, v163
	v_cmp_lt_i32_e32 vcc, v17, v16
	s_addc_u32 s1, s3, s1
	v_readlane_b32 s15, v251, 7
	v_cndmask_b32_e32 v17, v163, v17, vcc
	v_lshlrev_b32_e32 v25, 2, v17
	v_xor_b32_e32 v17, 16, v163
	v_cmp_lt_i32_e32 vcc, v17, v16
	s_ashr_i32 s15, s14, 31
	s_lshl_b64 s[4:5], s[12:13], 11
	v_cndmask_b32_e32 v17, v163, v17, vcc
	v_lshlrev_b32_e32 v26, 2, v17
	v_xor_b32_e32 v17, 32, v163
	v_cmp_lt_i32_e32 vcc, v17, v16
	v_mov_b32_e32 v21, v29
	v_readlane_b32 s16, v251, 4
	v_cndmask_b32_e32 v16, v163, v17, vcc
	v_lshlrev_b32_e32 v27, 2, v16
	v_lshl_add_u64 v[16:17], s[0:1], 0, v[28:29]
	s_mov_b64 s[0:1], 0x1ce80000
	v_lshl_add_u64 v[16:17], v[16:17], 0, s[0:1]
	s_lshl_b64 s[0:1], s[14:15], 6
	s_add_u32 s2, s2, s4
	v_lshlrev_b32_e32 v28, 4, v201
	s_addc_u32 s3, s3, s5
	v_lshl_add_u64 v[18:19], s[2:3], 0, v[28:29]
	s_mov_b64 s[2:3], 0xa380400
	v_lshl_add_u64 v[18:19], v[18:19], 0, s[2:3]
	s_lshl_b64 s[2:3], s[14:15], 11
	s_lshl_b64 s[4:5], s[12:13], 12
	s_add_u32 s4, s6, s4
	s_addc_u32 s5, s7, s5
	v_lshl_add_u64 v[20:21], s[4:5], 0, v[20:21]
	s_lshl_b64 s[4:5], s[14:15], 12
	v_mov_b32_e32 v28, 0x358637bd
	s_mov_b32 s8, 0x800000
	v_readlane_b32 s17, v251, 5
	v_mov_b32_e32 v29, 0
	s_and_saveexec_b64 s[6:7], s[16:17]
	global_load_dword v29, v[16:17], off
	s_or_b64 exec, exec, s[6:7]
	global_load_dwordx4 v[30:33], v[18:19], off offset:-1024
	global_load_dwordx4 v[34:37], v[18:19], off
	s_waitcnt vmcnt(0)
	s_branch .Lfn_body
.Lfn_loop:
	s_waitcnt vmcnt(4)
.Lfn_body:
	v_mov_b32_e32 v80, v29
	v_mov_b64_e32 v[56:57], v[30:31]
	v_mov_b64_e32 v[58:59], v[32:33]
	v_mov_b64_e32 v[60:61], v[34:35]
	v_mov_b64_e32 v[62:63], v[36:37]
	s_add_i32 s12, s12, s14
	v_lshl_add_u64 v[16:17], v[16:17], 0, s[0:1]
	v_lshl_add_u64 v[18:19], v[18:19], 0, s[2:3]
	s_cmp_lt_i32 s12, 0x8000
	s_cbranch_scc0 .Lfn_nopf
	v_mov_b32_e32 v29, 0
	s_and_saveexec_b64 s[6:7], s[16:17]
	global_load_dword v29, v[16:17], off
	s_or_b64 exec, exec, s[6:7]
	global_load_dwordx4 v[30:33], v[18:19], off offset:-1024
	global_load_dwordx4 v[34:37], v[18:19], off
.Lfn_nopf:
	s_nop 4
	s_nop 1
	v_add_f32_dpp v80, v80, v80 quad_perm:[1,0,3,2] row_mask:0xf bank_mask:0xf
	s_nop 1
	v_add_f32_dpp v80, v80, v80 quad_perm:[2,3,0,1] row_mask:0xf bank_mask:0xf
	s_nop 1
	v_add_f32_dpp v80, v80, v80 row_half_mirror row_mask:0xf bank_mask:0xf
	s_nop 1
	v_add_f32_dpp v80, v80, v80 row_mirror row_mask:0xf bank_mask:0xf
	v_mov_b32_e32 v81, v80
	s_nop 1
	v_permlane16_swap_b32_e32 v80, v81
	v_add_f32_e32 v80, v80, v81
	v_mov_b32_e32 v81, v80
	s_nop 1
	v_permlane32_swap_b32_e32 v80, v81
	v_add_f32_e32 v80, v80, v81
	v_fmamk_f32 v80, v80, 0x3a800000, v28
	v_mul_f32_e32 v81, 0x4b800000, v80
	v_cmp_gt_f32_e32 vcc, s8, v80
	v_lshlrev_b32_e32 v40, 16, v56
	v_and_b32_e32 v41, 0xffff0000, v56
	v_lshlrev_b32_e32 v42, 16, v57
	v_and_b32_e32 v43, 0xffff0000, v57
	v_lshlrev_b32_e32 v44, 16, v58
	v_and_b32_e32 v45, 0xffff0000, v58
	v_lshlrev_b32_e32 v46, 16, v59
	v_and_b32_e32 v47, 0xffff0000, v59
	v_cndmask_b32_e32 v80, v80, v81, vcc
	v_rsq_f32_e32 v80, v80
	v_lshlrev_b32_e32 v48, 16, v60
	v_and_b32_e32 v49, 0xffff0000, v60
	v_lshlrev_b32_e32 v50, 16, v61
	v_and_b32_e32 v51, 0xffff0000, v61
	v_lshlrev_b32_e32 v52, 16, v62
	v_and_b32_e32 v53, 0xffff0000, v62
	v_lshlrev_b32_e32 v54, 16, v63
	v_and_b32_e32 v55, 0xffff0000, v63
	v_mul_f32_e32 v81, 0x45800000, v80
	v_cndmask_b32_e32 v38, v80, v81, vcc
	v_pk_mul_f32 v[40:41], v[38:39], v[40:41] op_sel_hi:[0,1]
	v_pk_mul_f32 v[42:43], v[38:39], v[42:43] op_sel_hi:[0,1]
	v_pk_mul_f32 v[44:45], v[38:39], v[44:45] op_sel_hi:[0,1]
	v_pk_mul_f32 v[46:47], v[38:39], v[46:47] op_sel_hi:[0,1]
	v_pk_mul_f32 v[48:49], v[38:39], v[48:49] op_sel_hi:[0,1]
	v_pk_mul_f32 v[50:51], v[38:39], v[50:51] op_sel_hi:[0,1]
	v_pk_mul_f32 v[52:53], v[38:39], v[52:53] op_sel_hi:[0,1]
	v_pk_mul_f32 v[54:55], v[38:39], v[54:55] op_sel_hi:[0,1]
	v_pk_mul_f32 v[64:65], v[4:5], v[40:41]
	v_pk_mul_f32 v[66:67], v[6:7], v[42:43]
	v_pk_mul_f32 v[68:69], v[0:1], v[44:45]
	v_pk_mul_f32 v[70:71], v[2:3], v[46:47]
	v_pk_mul_f32 v[72:73], v[12:13], v[48:49]
	v_pk_mul_f32 v[74:75], v[14:15], v[50:51]
	v_pk_mul_f32 v[76:77], v[8:9], v[52:53]
	v_pk_mul_f32 v[78:79], v[10:11], v[54:55]
	global_store_dwordx4 v[20:21], v[64:67], off nt
	global_store_dwordx4 v[20:21], v[68:71], off offset:16 nt
	global_store_dwordx4 v[20:21], v[72:75], off offset:2048 nt
	global_store_dwordx4 v[20:21], v[76:79], off offset:2064 nt
	v_lshl_add_u64 v[20:21], v[20:21], 0, s[4:5]
	s_cmp_lt_i32 s12, 0x8000
	s_cbranch_scc1 .Lfn_loop
